# phase-1 modnorm (f32 rows -> bf16 H0) rewritten in block form: 4 rows per block, shift/scale loaded once per block, DPP row-sum reduction
# speedup vs baseline: 1.0078x; 1.0078x over previous
; __device__ __forceinline__ const float* inp(int k) { const CAS cfptr* p = (const CAS cfptr*)__builtin_amdgcn_kernarg_segment_ptr(); asm volatile("" : "+s"(p)); return p[k]; }
; #define LANE_IDS() const int f_tid = tid_(); const int f_lane = f_tid & 63; const int f_gtid = blockIdx.x * (NWAVES * 64) + f_tid; (void)f_lane; (void)f_gtid
; #define IN(k) ((((PH_MASK) >> (k)) & 1u) && kargs()->ph_lo <= (k) && (k) < kargs()->ph_hi)
; #define SEAM(k) do { if (IN((k) + 1)) xcd_barrier(xbar); } while (0)
; #define PH_PTRS() unsigned char* ws = kargs()->ws; F.ws = ws; F.out = kargs()->out; float* mod = (float*)(ws + WS_MOD); const float* mod1 = mod + 9 * MODS; bf16* X = (bf16*)(ws + WS_X);     bf16* H = (bf16*)(ws + WS_H); (void)mod; (void)mod1; (void)X; (void)H
;     LANE_IDS();
;     if (F.gw >= wave0) for (int row = row_begin + (F.gw - wave0); row < nrows; row += F.NGW - wave0) {
;         const bool isctx = row >= NLAT; const int b = isctx ? 8 : (row >> 12);
;         const size_t roff = isctx ? (size_t)(row - NLAT) * DM : (size_t)row * DM; const void* sp = isctx ? src_ctx : src_lat;
;         f32x4 v[4]; float ss = 0.f;
;         if (SB) { const u32x2* xr = (const u32x2*)((const bf16*)sp + roff) + f_lane;
; #pragma unroll
;             for (int j = 0; j < 4; ++j) { const u32x2 r = xr[64 * j]; v[j] = (f32x4){__uint_as_float(r.x << 16), __uint_as_float(r.x & 0xffff0000u), __uint_as_float(r.y << 16), __uint_as_float(r.y & 0xffff0000u)}; } }
;         else { const f32x4* xr = (const f32x4*)((const float*)sp + roff) + f_lane;
; #pragma unroll
;             for (int j = 0; j < 4; ++j) v[j] = xr[64 * j]; }
;         if (part != nullptr && isctx) {
;             const f32x4* p0 = (const f32x4*)(part + (size_t)(row - NLAT) * DM) + f_lane; const f32x4* p1 = p0 + (size_t)NCTX * DM / 4; const f32x4* g4p = (const f32x4*)pgate + f_lane;
; #pragma unroll
;             for (int j = 0; j < 4; ++j) v[j] += g4p[64 * j] * (p0[64 * j] + p1[64 * j]); }
; #pragma unroll
;         for (int j = 0; j < 4; ++j) ss += (v[j].x * v[j].x + v[j].y * v[j].y) + (v[j].z * v[j].z + v[j].w * v[j].w);
; __global__ void __launch_bounds__(NWAVES * 64, 2) mk_fwd(Args args) {
;     ...
;     if (IN(1)) for (int rep_ = 0; rep_ < PH_REPS(1); ++rep_) { PH_PTRS(); modnorm_rows<false>(F, inp(0), inp(2), NTOK, H, inp(6), mod, 0, 1); if (rep_ == PH_REPS(1) - 1) SEAM(1); }
.LBB0_18:
	s_mov_b64 s[4:5], s[0:1]
	s_load_dword s3, s[4:5], 0xf8
	s_waitcnt lgkmcnt(0)
	s_cmp_gt_i32 s3, 1
	s_cbranch_scc1 .LBB0_240
	s_mov_b64 s[4:5], s[0:1]
	s_load_dword s3, s[4:5], 0xfc
	s_waitcnt lgkmcnt(0)
	s_cmp_lt_i32 s3, 2
	s_cbranch_scc1 .LBB0_240
	s_cmpk_gt_u32 s46, 0x87ff
	s_mov_b64 s[4:5], s[0:1]
	s_mov_b64 s[6:7], s[0:1]
	s_mov_b64 s[10:11], s[0:1]
	s_mov_b64 s[14:15], s[0:1]
	s_mov_b64 s[12:13], s[0:1]
	v_mov_b32_e32 v0, v188
	s_cbranch_scc1 .LBB0_23
	s_load_dwordx2 s[4:5], s[0:1], 0xf0
	s_load_dwordx2 s[6:7], s[0:1], 0x0
	s_load_dwordx2 s[8:9], s[0:1], 0x10
	s_load_dwordx2 s[10:11], s[0:1], 0x30
	v_and_b32_e32 v2, 63, v188
	v_lshlrev_b32_e32 v0, 4, v2
	v_lshlrev_b32_e32 v2, 3, v2
	v_mov_b32_e32 v3, 0x358637bd
	s_waitcnt lgkmcnt(0)
	global_load_dwordx4 v[64:67], v0, s[10:11] offset:0
	global_load_dwordx4 v[68:71], v0, s[10:11] offset:1024
	global_load_dwordx4 v[72:75], v0, s[10:11] offset:2048
	global_load_dwordx4 v[76:79], v0, s[10:11] offset:3072
	s_add_u32 s12, s4, 0x1000
	s_addc_u32 s13, s5, 0
	s_add_u32 s14, s4, 0xe800000
	s_addc_u32 s15, s5, 0
	s_mov_b32 s16, s46
.Lmn1_blk:
	s_lshl_b32 s17, s16, 2
	s_cmp_lt_i32 s17, 0x8000
	s_cbranch_scc0 .Lmn1_ctx
	s_lshl_b32 s3, s16, 14
	s_add_u32 s18, s6, s3
	s_addc_u32 s19, s7, 0
	s_ashr_i32 s3, s17, 12
	s_branch .Lmn1_src
.Lmn1_ctx:
	s_sub_i32 s3, s17, 0x8000
	s_lshl_b32 s3, s3, 12
	s_add_u32 s18, s8, s3
	s_addc_u32 s19, s9, 0
	s_mov_b32 s3, 8
.Lmn1_src:
	s_mul_i32 s3, s3, 0x6000
	s_add_u32 s20, s12, s3
	s_addc_u32 s21, s13, 0
	s_add_u32 s100, s20, 0x1000
	s_addc_u32 s101, s21, 0
	global_load_dwordx4 v[120:123], v0, s[20:21] offset:0
	global_load_dwordx4 v[124:127], v0, s[20:21] offset:1024
	global_load_dwordx4 v[128:131], v0, s[20:21] offset:2048
	global_load_dwordx4 v[132:135], v0, s[20:21] offset:3072
	global_load_dwordx4 v[104:107], v0, s[100:101] offset:0
	global_load_dwordx4 v[108:111], v0, s[100:101] offset:1024
	global_load_dwordx4 v[112:115], v0, s[100:101] offset:2048
	global_load_dwordx4 v[116:119], v0, s[100:101] offset:3072
	global_load_dwordx4 v[8:11], v0, s[18:19] offset:0
	global_load_dwordx4 v[12:15], v0, s[18:19] offset:1024
	global_load_dwordx4 v[16:19], v0, s[18:19] offset:2048
	global_load_dwordx4 v[20:23], v0, s[18:19] offset:3072
	s_add_u32 s18, s18, 0x1000
	s_addc_u32 s19, s19, 0
	global_load_dwordx4 v[24:27], v0, s[18:19] offset:0
	global_load_dwordx4 v[28:31], v0, s[18:19] offset:1024
	global_load_dwordx4 v[32:35], v0, s[18:19] offset:2048
	global_load_dwordx4 v[36:39], v0, s[18:19] offset:3072
	s_add_u32 s18, s18, 0x1000
	s_addc_u32 s19, s19, 0
	global_load_dwordx4 v[40:43], v0, s[18:19] offset:0
	global_load_dwordx4 v[44:47], v0, s[18:19] offset:1024
	global_load_dwordx4 v[48:51], v0, s[18:19] offset:2048
	global_load_dwordx4 v[52:55], v0, s[18:19] offset:3072
	s_add_u32 s18, s18, 0x1000
	s_addc_u32 s19, s19, 0
	global_load_dwordx4 v[80:83], v0, s[18:19] offset:0
	global_load_dwordx4 v[84:87], v0, s[18:19] offset:1024
	global_load_dwordx4 v[88:91], v0, s[18:19] offset:2048
	global_load_dwordx4 v[92:95], v0, s[18:19] offset:3072
	s_waitcnt vmcnt(0)
	v_add_f32_e32 v104, 1.0, v104
	v_add_f32_e32 v105, 1.0, v105
	v_add_f32_e32 v106, 1.0, v106
	v_add_f32_e32 v107, 1.0, v107
	v_add_f32_e32 v108, 1.0, v108
	v_add_f32_e32 v109, 1.0, v109
	v_add_f32_e32 v110, 1.0, v110
	v_add_f32_e32 v111, 1.0, v111
	v_add_f32_e32 v112, 1.0, v112
	v_add_f32_e32 v113, 1.0, v113
	v_add_f32_e32 v114, 1.0, v114
	v_add_f32_e32 v115, 1.0, v115
	v_add_f32_e32 v116, 1.0, v116
	v_add_f32_e32 v117, 1.0, v117
	v_add_f32_e32 v118, 1.0, v118
	v_add_f32_e32 v119, 1.0, v119
	v_mul_f32_e32 v96, v8, v8
	v_mul_f32_e32 v100, v9, v9
	v_fmac_f32_e32 v96, v10, v10
	v_fmac_f32_e32 v100, v11, v11
	v_fmac_f32_e32 v96, v12, v12
	v_fmac_f32_e32 v100, v13, v13
	v_fmac_f32_e32 v96, v14, v14
	v_fmac_f32_e32 v100, v15, v15
	v_fmac_f32_e32 v96, v16, v16
	v_fmac_f32_e32 v100, v17, v17
	v_fmac_f32_e32 v96, v18, v18
	v_fmac_f32_e32 v100, v19, v19
	v_fmac_f32_e32 v96, v20, v20
	v_fmac_f32_e32 v100, v21, v21
	v_fmac_f32_e32 v96, v22, v22
	v_fmac_f32_e32 v100, v23, v23
	v_add_f32_e32 v96, v96, v100
	v_mul_f32_e32 v97, v24, v24
	v_mul_f32_e32 v100, v25, v25
	v_fmac_f32_e32 v97, v26, v26
	v_fmac_f32_e32 v100, v27, v27
	v_fmac_f32_e32 v97, v28, v28
	v_fmac_f32_e32 v100, v29, v29
	v_fmac_f32_e32 v97, v30, v30
	v_fmac_f32_e32 v100, v31, v31
	v_fmac_f32_e32 v97, v32, v32
	v_fmac_f32_e32 v100, v33, v33
	v_fmac_f32_e32 v97, v34, v34
	v_fmac_f32_e32 v100, v35, v35
	v_fmac_f32_e32 v97, v36, v36
	v_fmac_f32_e32 v100, v37, v37
	v_fmac_f32_e32 v97, v38, v38
	v_fmac_f32_e32 v100, v39, v39
	v_add_f32_e32 v97, v97, v100
	v_mul_f32_e32 v98, v40, v40
	v_mul_f32_e32 v100, v41, v41
	v_fmac_f32_e32 v98, v42, v42
	v_fmac_f32_e32 v100, v43, v43
	v_fmac_f32_e32 v98, v44, v44
	v_fmac_f32_e32 v100, v45, v45
	v_fmac_f32_e32 v98, v46, v46
	v_fmac_f32_e32 v100, v47, v47
	v_fmac_f32_e32 v98, v48, v48
	v_fmac_f32_e32 v100, v49, v49
	v_fmac_f32_e32 v98, v50, v50
	v_fmac_f32_e32 v100, v51, v51
	v_fmac_f32_e32 v98, v52, v52
	v_fmac_f32_e32 v100, v53, v53
	v_fmac_f32_e32 v98, v54, v54
	v_fmac_f32_e32 v100, v55, v55
	v_add_f32_e32 v98, v98, v100
	v_mul_f32_e32 v99, v80, v80
	v_mul_f32_e32 v100, v81, v81
	v_fmac_f32_e32 v99, v82, v82
	v_fmac_f32_e32 v100, v83, v83
	v_fmac_f32_e32 v99, v84, v84
	v_fmac_f32_e32 v100, v85, v85
	v_fmac_f32_e32 v99, v86, v86
	v_fmac_f32_e32 v100, v87, v87
	v_fmac_f32_e32 v99, v88, v88
	v_fmac_f32_e32 v100, v89, v89
	v_fmac_f32_e32 v99, v90, v90
	v_fmac_f32_e32 v100, v91, v91
	v_fmac_f32_e32 v99, v92, v92
	v_fmac_f32_e32 v100, v93, v93
	v_fmac_f32_e32 v99, v94, v94
	v_fmac_f32_e32 v100, v95, v95
	v_add_f32_e32 v99, v99, v100
; __device__ __forceinline__ unsigned cvt_pk_bf16(float lo, float hi) { unsigned r; asm volatile("v_cvt_pk_bf16_f32 %0, %1, %2" : "=v"(r) : "v"(lo), "v"(hi)); return r; }
;     ...
;         for (int j = 0; j < 4; ++j) ss += (v[j].x * v[j].x + v[j].y * v[j].y) + (v[j].z * v[j].z + v[j].w * v[j].w);
;         const float rstd = rsqrtf(wave_sum(ss) * (1.0f / DM) + EPS);
;         const f32x4* g4 = (const f32x4*)gnorm + f_lane; const f32x4* sh4 = (const f32x4*)(modl + b * MODS + shc * DM) + f_lane; const f32x4* sc4 = (const f32x4*)(modl + b * MODS + scc * DM) + f_lane;
;         u32x2* o8 = (u32x2*)(H + (size_t)row * DM) + f_lane;
; #pragma unroll
;         for (int j = 0; j < 4; ++j) { const f32x4 y = v[j] * rstd * g4[64 * j] * (sc4[64 * j] + 1.0f) + sh4[64 * j];
;             u32x2 w; w.x = cvt_pk_bf16(y.x, y.y); w.y = cvt_pk_bf16(y.z, y.w); o8[64 * j] = w; }
	v_add_f32_dpp v96, v96, v96 row_shr:1 row_mask:0xf bank_mask:0xf bound_ctrl:0
	v_add_f32_dpp v97, v97, v97 row_shr:1 row_mask:0xf bank_mask:0xf bound_ctrl:0
	v_add_f32_dpp v98, v98, v98 row_shr:1 row_mask:0xf bank_mask:0xf bound_ctrl:0
	v_add_f32_dpp v99, v99, v99 row_shr:1 row_mask:0xf bank_mask:0xf bound_ctrl:0
	v_add_f32_dpp v96, v96, v96 row_shr:2 row_mask:0xf bank_mask:0xf bound_ctrl:0
	v_add_f32_dpp v97, v97, v97 row_shr:2 row_mask:0xf bank_mask:0xf bound_ctrl:0
	v_add_f32_dpp v98, v98, v98 row_shr:2 row_mask:0xf bank_mask:0xf bound_ctrl:0
	v_add_f32_dpp v99, v99, v99 row_shr:2 row_mask:0xf bank_mask:0xf bound_ctrl:0
	v_add_f32_dpp v96, v96, v96 row_shr:4 row_mask:0xf bank_mask:0xf bound_ctrl:0
	v_add_f32_dpp v97, v97, v97 row_shr:4 row_mask:0xf bank_mask:0xf bound_ctrl:0
	v_add_f32_dpp v98, v98, v98 row_shr:4 row_mask:0xf bank_mask:0xf bound_ctrl:0
	v_add_f32_dpp v99, v99, v99 row_shr:4 row_mask:0xf bank_mask:0xf bound_ctrl:0
	v_add_f32_dpp v96, v96, v96 row_shr:8 row_mask:0xf bank_mask:0xf bound_ctrl:0
	v_add_f32_dpp v97, v97, v97 row_shr:8 row_mask:0xf bank_mask:0xf bound_ctrl:0
	v_add_f32_dpp v98, v98, v98 row_shr:8 row_mask:0xf bank_mask:0xf bound_ctrl:0
	v_add_f32_dpp v99, v99, v99 row_shr:8 row_mask:0xf bank_mask:0xf bound_ctrl:0
	v_add_f32_dpp v96, v96, v96 row_bcast:15 row_mask:0xa bank_mask:0xf
	v_add_f32_dpp v97, v97, v97 row_bcast:15 row_mask:0xa bank_mask:0xf
	v_add_f32_dpp v98, v98, v98 row_bcast:15 row_mask:0xa bank_mask:0xf
	v_add_f32_dpp v99, v99, v99 row_bcast:15 row_mask:0xa bank_mask:0xf
	v_add_f32_dpp v96, v96, v96 row_bcast:31 row_mask:0xc bank_mask:0xf
	v_add_f32_dpp v97, v97, v97 row_bcast:31 row_mask:0xc bank_mask:0xf
	v_add_f32_dpp v98, v98, v98 row_bcast:31 row_mask:0xc bank_mask:0xf
	v_add_f32_dpp v99, v99, v99 row_bcast:31 row_mask:0xc bank_mask:0xf
	s_nop 0
	v_readlane_b32 s47, v96, 63
	v_readlane_b32 s77, v97, 63
	v_readlane_b32 vcc_lo, v98, 63
	v_readlane_b32 vcc_hi, v99, 63
	s_lshl_b32 s3, s17, 11
	s_add_u32 s18, s14, s3
	s_addc_u32 s19, s15, 0
	v_mov_b32_e32 v102, s47
	v_fmamk_f32 v102, v102, 0x3a800000, v3
	v_rsq_f32_e32 v101, v102
	s_nop 0
	v_mul_f32_e32 v8, v8, v101
	v_mul_f32_e32 v9, v9, v101
	v_mul_f32_e32 v10, v10, v101
	v_mul_f32_e32 v11, v11, v101
	v_mul_f32_e32 v8, v64, v8
	v_mul_f32_e32 v9, v65, v9
	v_mul_f32_e32 v10, v66, v10
	v_mul_f32_e32 v11, v67, v11
	v_fma_f32 v8, v104, v8, v120
	v_fma_f32 v9, v105, v9, v121
	v_fma_f32 v10, v106, v10, v122
	v_fma_f32 v11, v107, v11, v123
	v_cvt_pk_bf16_f32 v56, v8, v9
	v_cvt_pk_bf16_f32 v57, v10, v11
	global_store_dwordx2 v2, v[56:57], s[18:19] offset:0
	v_mul_f32_e32 v12, v12, v101
	v_mul_f32_e32 v13, v13, v101
	v_mul_f32_e32 v14, v14, v101
	v_mul_f32_e32 v15, v15, v101
	v_mul_f32_e32 v12, v68, v12
	v_mul_f32_e32 v13, v69, v13
	v_mul_f32_e32 v14, v70, v14
	v_mul_f32_e32 v15, v71, v15
	v_fma_f32 v12, v108, v12, v124
	v_fma_f32 v13, v109, v13, v125
	v_fma_f32 v14, v110, v14, v126
	v_fma_f32 v15, v111, v15, v127
	v_cvt_pk_bf16_f32 v56, v12, v13
	v_cvt_pk_bf16_f32 v57, v14, v15
	global_store_dwordx2 v2, v[56:57], s[18:19] offset:512
	v_mul_f32_e32 v16, v16, v101
	v_mul_f32_e32 v17, v17, v101
	v_mul_f32_e32 v18, v18, v101
	v_mul_f32_e32 v19, v19, v101
	v_mul_f32_e32 v16, v72, v16
	v_mul_f32_e32 v17, v73, v17
	v_mul_f32_e32 v18, v74, v18
	v_mul_f32_e32 v19, v75, v19
	v_fma_f32 v16, v112, v16, v128
	v_fma_f32 v17, v113, v17, v129
	v_fma_f32 v18, v114, v18, v130
	v_fma_f32 v19, v115, v19, v131
	v_cvt_pk_bf16_f32 v56, v16, v17
	v_cvt_pk_bf16_f32 v57, v18, v19
	global_store_dwordx2 v2, v[56:57], s[18:19] offset:1024
	v_mul_f32_e32 v20, v20, v101
	v_mul_f32_e32 v21, v21, v101
	v_mul_f32_e32 v22, v22, v101
	v_mul_f32_e32 v23, v23, v101
	v_mul_f32_e32 v20, v76, v20
	v_mul_f32_e32 v21, v77, v21
	v_mul_f32_e32 v22, v78, v22
	v_mul_f32_e32 v23, v79, v23
	v_fma_f32 v20, v116, v20, v132
	v_fma_f32 v21, v117, v21, v133
	v_fma_f32 v22, v118, v22, v134
	v_fma_f32 v23, v119, v23, v135
	v_cvt_pk_bf16_f32 v56, v20, v21
	v_cvt_pk_bf16_f32 v57, v22, v23
	global_store_dwordx2 v2, v[56:57], s[18:19] offset:1536
	v_mov_b32_e32 v102, s77
	v_fmamk_f32 v102, v102, 0x3a800000, v3
	v_rsq_f32_e32 v101, v102
	s_add_u32 s18, s18, 0x800
	s_addc_u32 s19, s19, 0
	v_mul_f32_e32 v24, v24, v101
	v_mul_f32_e32 v25, v25, v101
	v_mul_f32_e32 v26, v26, v101
	v_mul_f32_e32 v27, v27, v101
	v_mul_f32_e32 v24, v64, v24
	v_mul_f32_e32 v25, v65, v25
	v_mul_f32_e32 v26, v66, v26
	v_mul_f32_e32 v27, v67, v27
	v_fma_f32 v24, v104, v24, v120
	v_fma_f32 v25, v105, v25, v121
	v_fma_f32 v26, v106, v26, v122
	v_fma_f32 v27, v107, v27, v123
	v_cvt_pk_bf16_f32 v56, v24, v25
	v_cvt_pk_bf16_f32 v57, v26, v27
	global_store_dwordx2 v2, v[56:57], s[18:19] offset:0
	v_mul_f32_e32 v28, v28, v101
	v_mul_f32_e32 v29, v29, v101
	v_mul_f32_e32 v30, v30, v101
	v_mul_f32_e32 v31, v31, v101
	v_mul_f32_e32 v28, v68, v28
	v_mul_f32_e32 v29, v69, v29
	v_mul_f32_e32 v30, v70, v30
	v_mul_f32_e32 v31, v71, v31
	v_fma_f32 v28, v108, v28, v124
	v_fma_f32 v29, v109, v29, v125
	v_fma_f32 v30, v110, v30, v126
	v_fma_f32 v31, v111, v31, v127
	v_cvt_pk_bf16_f32 v56, v28, v29
	v_cvt_pk_bf16_f32 v57, v30, v31
	global_store_dwordx2 v2, v[56:57], s[18:19] offset:512
	v_mul_f32_e32 v32, v32, v101
	v_mul_f32_e32 v33, v33, v101
; __device__ __forceinline__ unsigned cvt_pk_bf16(float lo, float hi) { unsigned r; asm volatile("v_cvt_pk_bf16_f32 %0, %1, %2" : "=v"(r) : "v"(lo), "v"(hi)); return r; }
;     ...
;     if (F.gw >= wave0) for (int row = row_begin + (F.gw - wave0); row < nrows; row += F.NGW - wave0) {
;     ...
;         for (int j = 0; j < 4; ++j) { const f32x4 y = v[j] * rstd * g4[64 * j] * (sc4[64 * j] + 1.0f) + sh4[64 * j];
;             u32x2 w; w.x = cvt_pk_bf16(y.x, y.y); w.y = cvt_pk_bf16(y.z, y.w); o8[64 * j] = w; }
	v_mul_f32_e32 v34, v34, v101
	v_mul_f32_e32 v35, v35, v101
	v_mul_f32_e32 v32, v72, v32
	v_mul_f32_e32 v33, v73, v33
	v_mul_f32_e32 v34, v74, v34
	v_mul_f32_e32 v35, v75, v35
	v_fma_f32 v32, v112, v32, v128
	v_fma_f32 v33, v113, v33, v129
	v_fma_f32 v34, v114, v34, v130
	v_fma_f32 v35, v115, v35, v131
	v_cvt_pk_bf16_f32 v56, v32, v33
	v_cvt_pk_bf16_f32 v57, v34, v35
	global_store_dwordx2 v2, v[56:57], s[18:19] offset:1024
	v_mul_f32_e32 v36, v36, v101
	v_mul_f32_e32 v37, v37, v101
	v_mul_f32_e32 v38, v38, v101
	v_mul_f32_e32 v39, v39, v101
	v_mul_f32_e32 v36, v76, v36
	v_mul_f32_e32 v37, v77, v37
	v_mul_f32_e32 v38, v78, v38
	v_mul_f32_e32 v39, v79, v39
	v_fma_f32 v36, v116, v36, v132
	v_fma_f32 v37, v117, v37, v133
	v_fma_f32 v38, v118, v38, v134
	v_fma_f32 v39, v119, v39, v135
	v_cvt_pk_bf16_f32 v56, v36, v37
	v_cvt_pk_bf16_f32 v57, v38, v39
	global_store_dwordx2 v2, v[56:57], s[18:19] offset:1536
	v_mov_b32_e32 v102, vcc_lo
	v_fmamk_f32 v102, v102, 0x3a800000, v3
	v_rsq_f32_e32 v101, v102
	s_add_u32 s18, s18, 0x800
	s_addc_u32 s19, s19, 0
	v_mul_f32_e32 v40, v40, v101
	v_mul_f32_e32 v41, v41, v101
	v_mul_f32_e32 v42, v42, v101
	v_mul_f32_e32 v43, v43, v101
	v_mul_f32_e32 v40, v64, v40
	v_mul_f32_e32 v41, v65, v41
	v_mul_f32_e32 v42, v66, v42
	v_mul_f32_e32 v43, v67, v43
	v_fma_f32 v40, v104, v40, v120
	v_fma_f32 v41, v105, v41, v121
	v_fma_f32 v42, v106, v42, v122
	v_fma_f32 v43, v107, v43, v123
	v_cvt_pk_bf16_f32 v56, v40, v41
	v_cvt_pk_bf16_f32 v57, v42, v43
	global_store_dwordx2 v2, v[56:57], s[18:19] offset:0
	v_mul_f32_e32 v44, v44, v101
	v_mul_f32_e32 v45, v45, v101
	v_mul_f32_e32 v46, v46, v101
	v_mul_f32_e32 v47, v47, v101
	v_mul_f32_e32 v44, v68, v44
	v_mul_f32_e32 v45, v69, v45
	v_mul_f32_e32 v46, v70, v46
	v_mul_f32_e32 v47, v71, v47
	v_fma_f32 v44, v108, v44, v124
	v_fma_f32 v45, v109, v45, v125
	v_fma_f32 v46, v110, v46, v126
	v_fma_f32 v47, v111, v47, v127
	v_cvt_pk_bf16_f32 v56, v44, v45
	v_cvt_pk_bf16_f32 v57, v46, v47
	global_store_dwordx2 v2, v[56:57], s[18:19] offset:512
	v_mul_f32_e32 v48, v48, v101
	v_mul_f32_e32 v49, v49, v101
	v_mul_f32_e32 v50, v50, v101
	v_mul_f32_e32 v51, v51, v101
	v_mul_f32_e32 v48, v72, v48
	v_mul_f32_e32 v49, v73, v49
	v_mul_f32_e32 v50, v74, v50
	v_mul_f32_e32 v51, v75, v51
	v_fma_f32 v48, v112, v48, v128
	v_fma_f32 v49, v113, v49, v129
	v_fma_f32 v50, v114, v50, v130
	v_fma_f32 v51, v115, v51, v131
	v_cvt_pk_bf16_f32 v56, v48, v49
	v_cvt_pk_bf16_f32 v57, v50, v51
	global_store_dwordx2 v2, v[56:57], s[18:19] offset:1024
	v_mul_f32_e32 v52, v52, v101
	v_mul_f32_e32 v53, v53, v101
	v_mul_f32_e32 v54, v54, v101
	v_mul_f32_e32 v55, v55, v101
	v_mul_f32_e32 v52, v76, v52
	v_mul_f32_e32 v53, v77, v53
	v_mul_f32_e32 v54, v78, v54
	v_mul_f32_e32 v55, v79, v55
	v_fma_f32 v52, v116, v52, v132
	v_fma_f32 v53, v117, v53, v133
	v_fma_f32 v54, v118, v54, v134
	v_fma_f32 v55, v119, v55, v135
	v_cvt_pk_bf16_f32 v56, v52, v53
	v_cvt_pk_bf16_f32 v57, v54, v55
	global_store_dwordx2 v2, v[56:57], s[18:19] offset:1536
	v_mov_b32_e32 v102, vcc_hi
	v_fmamk_f32 v102, v102, 0x3a800000, v3
	v_rsq_f32_e32 v101, v102
	s_add_u32 s18, s18, 0x800
	s_addc_u32 s19, s19, 0
	v_mul_f32_e32 v80, v80, v101
	v_mul_f32_e32 v81, v81, v101
	v_mul_f32_e32 v82, v82, v101
	v_mul_f32_e32 v83, v83, v101
	v_mul_f32_e32 v80, v64, v80
	v_mul_f32_e32 v81, v65, v81
	v_mul_f32_e32 v82, v66, v82
	v_mul_f32_e32 v83, v67, v83
	v_fma_f32 v80, v104, v80, v120
	v_fma_f32 v81, v105, v81, v121
	v_fma_f32 v82, v106, v82, v122
	v_fma_f32 v83, v107, v83, v123
	v_cvt_pk_bf16_f32 v56, v80, v81
	v_cvt_pk_bf16_f32 v57, v82, v83
	global_store_dwordx2 v2, v[56:57], s[18:19] offset:0
	v_mul_f32_e32 v84, v84, v101
	v_mul_f32_e32 v85, v85, v101
	v_mul_f32_e32 v86, v86, v101
	v_mul_f32_e32 v87, v87, v101
	v_mul_f32_e32 v84, v68, v84
	v_mul_f32_e32 v85, v69, v85
	v_mul_f32_e32 v86, v70, v86
	v_mul_f32_e32 v87, v71, v87
	v_fma_f32 v84, v108, v84, v124
	v_fma_f32 v85, v109, v85, v125
	v_fma_f32 v86, v110, v86, v126
	v_fma_f32 v87, v111, v87, v127
	v_cvt_pk_bf16_f32 v56, v84, v85
	v_cvt_pk_bf16_f32 v57, v86, v87
	global_store_dwordx2 v2, v[56:57], s[18:19] offset:512
	v_mul_f32_e32 v88, v88, v101
	v_mul_f32_e32 v89, v89, v101
	v_mul_f32_e32 v90, v90, v101
	v_mul_f32_e32 v91, v91, v101
	v_mul_f32_e32 v88, v72, v88
	v_mul_f32_e32 v89, v73, v89
	v_mul_f32_e32 v90, v74, v90
	v_mul_f32_e32 v91, v75, v91
	v_fma_f32 v88, v112, v88, v128
	v_fma_f32 v89, v113, v89, v129
	v_fma_f32 v90, v114, v90, v130
	v_fma_f32 v91, v115, v91, v131
	v_cvt_pk_bf16_f32 v56, v88, v89
	v_cvt_pk_bf16_f32 v57, v90, v91
	global_store_dwordx2 v2, v[56:57], s[18:19] offset:1024
	v_mul_f32_e32 v92, v92, v101
	v_mul_f32_e32 v93, v93, v101
	v_mul_f32_e32 v94, v94, v101
	v_mul_f32_e32 v95, v95, v101
	v_mul_f32_e32 v92, v76, v92
	v_mul_f32_e32 v93, v77, v93
	v_mul_f32_e32 v94, v78, v94
	v_mul_f32_e32 v95, v79, v95
	v_fma_f32 v92, v116, v92, v132
	v_fma_f32 v93, v117, v93, v133
	v_fma_f32 v94, v118, v94, v134
	v_fma_f32 v95, v119, v95, v135
	v_cvt_pk_bf16_f32 v56, v92, v93
	v_cvt_pk_bf16_f32 v57, v94, v95
	global_store_dwordx2 v2, v[56:57], s[18:19] offset:1536
	s_add_i32 s16, s16, s76
	s_lshl_b32 s17, s16, 2
	s_cmp_lt_i32 s17, 0x8800
	s_cbranch_scc1 .Lmn1_blk
	s_ashr_i32 s47, s46, 31
	s_ashr_i32 s77, s76, 31
